# MLA: no per-slot running-max/rescale check after the first tile (shift fixed at the first tile's row max); non-finite l or O at unit end -> workgroup vote -> unit redone by the checked code path
# speedup vs baseline: 1.0155x; 1.0155x over previous
.LBB0_1885:
	s_or_b64 exec, exec, s[0:1]
	v_readlane_b32 s0, v250, 2
	v_readlane_b32 s1, v250, 3
	v_readlane_b32 s86, v250, 1
	s_andn2_b64 vcc, exec, s[0:1]
	s_waitcnt vmcnt(0) lgkmcnt(0)
	s_barrier
	s_cbranch_vccnz .LBB0_1920
	v_and_b32_e32 v234, 31, v0
	v_bfe_u32 v235, v0, 5, 1
	v_mul_u32_u24_e32 v220, 0xd0, v234
	v_lshl_add_u32 v220, v235, 4, v220
	v_mul_u32_u24_e32 v221, 0x88, v234
	v_lshl_add_u32 v221, v235, 3, v221
	v_add_u32_e32 v221, 0xd000, v221
	v_lshl_or_b32 v1, s87, 5, v234
	v_mul_u32_u24_e32 v237, 0xc0, v1
	v_lshl_add_u32 v237, v235, 4, v237
	v_lshlrev_b32_e32 v236, 10, v1
	v_lshl_add_u32 v236, v235, 3, v236
	v_lshlrev_b32_e32 v226, 4, v0
	v_add_u32_e32 v227, 0x2000, v226
	v_add_u32_e32 v228, 0x4000, v226
	v_lshrrev_b32_e32 v234, 3, v0
	v_and_b32_e32 v235, 7, v0
	v_mul_u32_u24_e32 v229, 0x2200, v234
	v_lshl_add_u32 v229, v235, 4, v229
	v_mul_u32_u24_e32 v225, 0x88, v234
	v_lshl_add_u32 v225, v235, 4, v225
	v_add_u32_e32 v225, 0xd000, v225
	s_mov_b32 s17, 0xaaab
	s_movk_i32 s18, 0xd0
	v_mov_b32_e32 v234, v0
	v_mul_lo_u32 v235, v234, s17
	v_lshrrev_b32_e32 v235, 19, v235
	v_mul_u32_u24_e32 v1, 12, v235
	v_sub_u32_e32 v234, v234, v1
	v_lshrrev_b32_e32 v1, 6, v235
	v_and_b32_e32 v235, 63, v235
	v_mul_u32_u24_e32 v1, 0x3400, v1
	v_mad_u32_u24 v1, v235, s18, v1
	v_lshl_add_u32 v222, v234, 4, v1
	v_add_u32_e32 v234, 512, v0
	v_mul_lo_u32 v235, v234, s17
	v_lshrrev_b32_e32 v235, 19, v235
	v_mul_u32_u24_e32 v1, 12, v235
	v_sub_u32_e32 v234, v234, v1
	v_lshrrev_b32_e32 v1, 6, v235
	v_and_b32_e32 v235, 63, v235
	v_mul_u32_u24_e32 v1, 0x3400, v1
	v_mad_u32_u24 v1, v235, s18, v1
	v_lshl_add_u32 v223, v234, 4, v1
	v_add_u32_e32 v234, 1024, v0
	v_mul_lo_u32 v235, v234, s17
	v_lshrrev_b32_e32 v235, 19, v235
	v_mul_u32_u24_e32 v1, 12, v235
	v_sub_u32_e32 v234, v234, v1
	v_lshrrev_b32_e32 v1, 6, v235
	v_and_b32_e32 v235, 63, v235
	v_mul_u32_u24_e32 v1, 0x3400, v1
	v_mad_u32_u24 v1, v235, s18, v1
	v_lshl_add_u32 v224, v234, 4, v1
	v_mov_b32_e32 v234, 0
	v_mov_b32_e32 v235, 0x186a0
	ds_write_b32 v235, v234
.Lmla_restart:
	s_lshr_b32 s17, s2, 4
	s_and_b32 s18, s2, 15
	s_mul_i32 s19, s17, 0xcc000
	s_add_u32 s4, s78, s19
	s_addc_u32 s5, s79, 0
	s_mul_i32 s19, s17, 0x88000
	s_add_u32 s19, s19, 0x1a00000
	s_add_u32 s10, s78, s19
	s_addc_u32 s11, s79, 0
	s_lshl_b32 s19, s17, 12
	s_lshl_b32 s20, s18, 8
	s_add_u32 s19, s19, s20
	s_mul_i32 s19, s19, 0xc0
	s_add_u32 s19, s19, 0x1400000
	s_add_u32 s12, s80, s19
	s_addc_u32 s13, s81, 0
	s_lshr_b32 s19, s17, 3
	s_lshl_b32 s19, s19, 12
	s_add_u32 s19, s19, s20
	s_lshl_b32 s19, s19, 10
	s_and_b32 s21, s17, 7
	s_lshl_b32 s21, s21, 7
	s_add_u32 s19, s19, s21
	s_add_u32 s19, s19, 0x7900000
	s_add_u32 s14, s80, s19
	s_addc_u32 s15, s81, 0
	global_load_dwordx4 v[98:101], v237, s[12:13] offset:0
	global_load_dwordx4 v[102:105], v237, s[12:13] offset:32
	global_load_dwordx4 v[106:109], v237, s[12:13] offset:64
	global_load_dwordx4 v[110:113], v237, s[12:13] offset:96
	global_load_dwordx4 v[114:117], v237, s[12:13] offset:128
	global_load_dwordx4 v[118:121], v237, s[12:13] offset:160
	global_load_dwordx4 v[34:37], v226, s[4:5]
	global_load_dwordx4 v[38:41], v227, s[4:5]
	global_load_dwordx4 v[42:45], v228, s[4:5]
	global_load_dwordx4 v[46:49], v229, s[10:11]
	s_add_u32 s4, s4, 0x6000
	s_addc_u32 s5, s5, 0
	global_load_dwordx4 v[50:53], v226, s[4:5]
	global_load_dwordx4 v[54:57], v227, s[4:5]
	global_load_dwordx4 v[58:61], v228, s[4:5]
	global_load_dwordx4 v[62:65], v229, s[10:11] offset:128
	global_load_dwordx4 v[216:219], v229, s[10:11] offset:256
	s_add_u32 s4, s4, 0x6000
	s_addc_u32 s5, s5, 0
	s_add_u32 s10, s10, 0x180
	s_addc_u32 s11, s11, 0
	v_mov_b32_e32 v2, 0
	v_mov_b32_e32 v3, 0
	v_mov_b32_e32 v4, 0
	v_mov_b32_e32 v5, 0
	v_mov_b32_e32 v6, 0
	v_mov_b32_e32 v7, 0
	v_mov_b32_e32 v8, 0
	v_mov_b32_e32 v9, 0
	v_mov_b32_e32 v10, 0
	v_mov_b32_e32 v11, 0
	v_mov_b32_e32 v12, 0
	v_mov_b32_e32 v13, 0
	v_mov_b32_e32 v14, 0
	v_mov_b32_e32 v15, 0
	v_mov_b32_e32 v16, 0
	v_mov_b32_e32 v17, 0
	v_mov_b32_e32 v18, 0
	v_mov_b32_e32 v19, 0
	v_mov_b32_e32 v20, 0
	v_mov_b32_e32 v21, 0
	v_mov_b32_e32 v22, 0
	v_mov_b32_e32 v23, 0
	v_mov_b32_e32 v24, 0
	v_mov_b32_e32 v25, 0
	v_mov_b32_e32 v26, 0
	v_mov_b32_e32 v27, 0
	v_mov_b32_e32 v28, 0
	v_mov_b32_e32 v29, 0
	v_mov_b32_e32 v30, 0
	v_mov_b32_e32 v31, 0
	v_mov_b32_e32 v32, 0
	v_mov_b32_e32 v33, 0
	v_mov_b32_e32 v122, 0
	v_mov_b32_e32 v123, 0
	v_mov_b32_e32 v124, 0
	v_mov_b32_e32 v125, 0
	v_mov_b32_e32 v126, 0
	v_mov_b32_e32 v127, 0
	v_mov_b32_e32 v128, 0
	v_mov_b32_e32 v129, 0
	v_mov_b32_e32 v130, 0
	v_mov_b32_e32 v131, 0
	v_mov_b32_e32 v132, 0
	v_mov_b32_e32 v133, 0
	v_mov_b32_e32 v134, 0
	v_mov_b32_e32 v135, 0
	v_mov_b32_e32 v136, 0
	v_mov_b32_e32 v137, 0
	v_mov_b32_e32 v230, 0
	v_mov_b32_e32 v231, 0
	v_mov_b32_e32 v232, 0
	s_waitcnt vmcnt(5)
	ds_write_b128 v222, v[34:37]
	ds_write_b128 v223, v[38:41]
	ds_write_b128 v224, v[42:45]
	ds_write_b64 v225, v[46:47]
	ds_write_b64 v225, v[48:49] offset:8
	s_waitcnt vmcnt(1)
	ds_write_b128 v222, v[50:53] offset:26624
	ds_write_b128 v223, v[54:57] offset:26624
	ds_write_b128 v224, v[58:61] offset:26624
	ds_write_b64 v225, v[62:63] offset:8704
	ds_write_b64 v225, v[64:65] offset:8712
	s_waitcnt lgkmcnt(0)
	s_barrier

.Lmla_loop:
	v_exp_f32_e32 v34, v34
	v_exp_f32_e32 v35, v35
	v_exp_f32_e32 v36, v36
	s_waitcnt lgkmcnt(4)
	v_mfma_f32_32x32x16_bf16 v[66:81], v[138:141], v[98:101], v[122:137]
	ds_read_b128 v[138:141], v220 offset:13408
	v_exp_f32_e32 v37, v37
	v_add_f32_e32 v231, v231, v34
	v_add_f32_e32 v232, v232, v35
	v_exp_f32_e32 v38, v38
	v_mfma_f32_32x32x16_bf16 v[82:97], v[142:145], v[98:101], v[122:137]
	ds_read_b128 v[142:145], v220 offset:20064
	v_exp_f32_e32 v39, v39
	v_add_f32_e32 v231, v231, v36
	v_add_f32_e32 v232, v232, v37
	s_waitcnt lgkmcnt(4)
	v_mfma_f32_32x32x16_bf16 v[66:81], v[146:149], v[102:105], v[66:81]
	ds_read_b128 v[146:149], v220 offset:13440
	global_load_dwordx4 v[200:203], v226, s[4:5]
	global_load_dwordx4 v[204:207], v227, s[4:5]
	global_load_dwordx4 v[208:211], v228, s[4:5]
	s_add_u32 s4, s4, 0x6000
	s_addc_u32 s5, s5, 0
	global_load_dwordx4 v[212:215], v229, s[10:11]
	s_add_u32 s10, s10, 0x80
	s_addc_u32 s11, s11, 0
	v_exp_f32_e32 v40, v40
	v_exp_f32_e32 v41, v41
	v_add_f32_e32 v231, v231, v38
	v_add_f32_e32 v232, v232, v39
	v_mfma_f32_32x32x16_bf16 v[82:97], v[150:153], v[102:105], v[82:97]
	ds_read_b128 v[150:153], v220 offset:20096
	v_add_f32_e32 v231, v231, v40
	v_add_f32_e32 v232, v232, v41
	v_cvt_pk_bf16_f32 v34, v34, v35
	v_cvt_pk_bf16_f32 v35, v36, v37
	v_cvt_pk_bf16_f32 v36, v38, v39
	s_waitcnt lgkmcnt(4)
	v_mfma_f32_32x32x16_bf16 v[66:81], v[154:157], v[106:109], v[66:81]
	ds_read_b128 v[154:157], v220 offset:13472
	v_cvt_pk_bf16_f32 v37, v40, v41
	v_exp_f32_e32 v42, v42
	v_exp_f32_e32 v43, v43
	v_mfma_f32_32x32x16_bf16 v[82:97], v[158:161], v[106:109], v[82:97]
	ds_read_b128 v[158:161], v220 offset:20128
	v_exp_f32_e32 v44, v44
	v_exp_f32_e32 v45, v45
	v_add_f32_e32 v231, v231, v42
	v_add_f32_e32 v232, v232, v43
	s_waitcnt lgkmcnt(4)
	v_mfma_f32_32x32x16_bf16 v[66:81], v[138:141], v[110:113], v[66:81]
	ds_read_b64 v[162:163], v221 offset:0
	ds_read_b64 v[164:165], v221 offset:16
	v_exp_f32_e32 v46, v46
	v_exp_f32_e32 v47, v47
	v_add_f32_e32 v231, v231, v44
	v_mfma_f32_32x32x16_bf16 v[82:97], v[142:145], v[110:113], v[82:97]
	ds_read_b64 v[166:167], v221 offset:4352
	ds_read_b64 v[168:169], v221 offset:4368
	v_add_f32_e32 v232, v232, v45
	v_exp_f32_e32 v48, v48
	v_exp_f32_e32 v49, v49
	s_waitcnt lgkmcnt(6)
	v_mfma_f32_32x32x16_bf16 v[66:81], v[146:149], v[114:117], v[66:81]
	ds_read_b64 v[170:171], v221 offset:32
	ds_read_b64 v[172:173], v221 offset:48
	v_add_f32_e32 v231, v231, v46
	v_add_f32_e32 v232, v232, v47
	v_add_f32_e32 v231, v231, v48
	v_add_f32_e32 v232, v232, v49
	v_cvt_pk_bf16_f32 v42, v42, v43
	v_cvt_pk_bf16_f32 v43, v44, v45
	v_mfma_f32_32x32x16_bf16 v[82:97], v[150:153], v[114:117], v[82:97]
	ds_read_b64 v[174:175], v221 offset:4384
	ds_read_b64 v[176:177], v221 offset:4400
	v_cvt_pk_bf16_f32 v44, v46, v47
	v_cvt_pk_bf16_f32 v45, v48, v49
	v_exp_f32_e32 v50, v50
	v_exp_f32_e32 v51, v51
	s_waitcnt lgkmcnt(8)
	v_mfma_f32_32x32x16_bf16 v[66:81], v[154:157], v[118:121], v[66:81]
	ds_read_b64 v[180:181], v221 offset:64
	ds_read_b64 v[182:183], v221 offset:80
	v_exp_f32_e32 v52, v52
	v_exp_f32_e32 v53, v53
	v_mfma_f32_32x32x16_bf16 v[82:97], v[158:161], v[118:121], v[82:97]
	ds_read_b64 v[184:185], v221 offset:4416
	ds_read_b64 v[186:187], v221 offset:4432
	v_add_f32_e32 v231, v231, v50
	v_add_f32_e32 v232, v232, v51
	v_exp_f32_e32 v54, v54
	v_exp_f32_e32 v55, v55
	s_waitcnt lgkmcnt(8)
	v_mfma_f32_32x32x16_bf16 v[2:17], v[162:165], v[34:37], v[2:17]
	ds_read_b64 v[188:189], v221 offset:96
	ds_read_b64 v[190:191], v221 offset:112
	v_add_f32_e32 v231, v231, v52
	v_add_f32_e32 v232, v232, v53
	v_exp_f32_e32 v56, v56
	v_exp_f32_e32 v57, v57
	v_mfma_f32_32x32x16_bf16 v[18:33], v[166:169], v[34:37], v[18:33]
	ds_read_b64 v[192:193], v221 offset:4448
	ds_read_b64 v[194:195], v221 offset:4464
	v_add_f32_e32 v231, v231, v54
	v_add_f32_e32 v232, v232, v55
	v_add_f32_e32 v231, v231, v56
	v_add_f32_e32 v232, v232, v57
	s_waitcnt lgkmcnt(8)
	v_mfma_f32_32x32x16_bf16 v[2:17], v[170:173], v[42:45], v[2:17]
	v_cvt_pk_bf16_f32 v50, v50, v51
	v_cvt_pk_bf16_f32 v51, v52, v53
	v_cvt_pk_bf16_f32 v52, v54, v55
	v_cvt_pk_bf16_f32 v53, v56, v57
	v_exp_f32_e32 v58, v58
	v_mfma_f32_32x32x16_bf16 v[18:33], v[174:177], v[42:45], v[18:33]
	s_waitcnt vmcnt(4)
	ds_write_b64 v225, v[216:217] offset:17408
	ds_write_b64 v225, v[218:219] offset:17416
	v_exp_f32_e32 v59, v59
	v_exp_f32_e32 v60, v60
	v_exp_f32_e32 v61, v61
	s_waitcnt lgkmcnt(6)
	v_mfma_f32_32x32x16_bf16 v[2:17], v[180:183], v[50:53], v[2:17]
	v_add_f32_e32 v231, v231, v58
	v_add_f32_e32 v232, v232, v59
	v_exp_f32_e32 v62, v62
	v_mfma_f32_32x32x16_bf16 v[18:33], v[184:187], v[50:53], v[18:33]
	v_exp_f32_e32 v63, v63
	v_add_f32_e32 v231, v231, v60
	v_add_f32_e32 v232, v232, v61
	v_exp_f32_e32 v64, v64
	v_exp_f32_e32 v65, v65
	v_add_f32_e32 v231, v231, v62
	v_add_f32_e32 v232, v232, v63
	v_add_f32_e32 v231, v231, v64
	v_add_f32_e32 v232, v232, v65
	v_cvt_pk_bf16_f32 v58, v58, v59
	v_cvt_pk_bf16_f32 v59, v60, v61
	v_cvt_pk_bf16_f32 v60, v62, v63
	v_cvt_pk_bf16_f32 v61, v64, v65
	s_waitcnt lgkmcnt(2)
	s_nop 0
	v_mfma_f32_32x32x16_bf16 v[2:17], v[188:191], v[58:61], v[2:17]
	v_mfma_f32_32x32x16_bf16 v[18:33], v[192:195], v[58:61], v[18:33]
	ds_read_b128 v[138:141], v220 offset:26624
	ds_read_b128 v[142:145], v220 offset:33280
	ds_read_b128 v[146:149], v220 offset:26656
	ds_read_b128 v[150:153], v220 offset:33312
	ds_read_b128 v[154:157], v220 offset:26688
	ds_read_b128 v[158:161], v220 offset:33344
	s_waitcnt lgkmcnt(6)
	s_barrier
	v_exp_f32_e32 v66, v66
	v_exp_f32_e32 v67, v67
	v_exp_f32_e32 v68, v68
	s_waitcnt lgkmcnt(4)
	v_mfma_f32_32x32x16_bf16 v[34:49], v[138:141], v[98:101], v[122:137]
	ds_read_b128 v[138:141], v220 offset:26720
	v_exp_f32_e32 v69, v69
	v_add_f32_e32 v231, v231, v66
	v_add_f32_e32 v232, v232, v67
	v_exp_f32_e32 v70, v70
	v_mfma_f32_32x32x16_bf16 v[50:65], v[142:145], v[98:101], v[122:137]
	ds_read_b128 v[142:145], v220 offset:33376
	v_exp_f32_e32 v71, v71
	v_add_f32_e32 v231, v231, v68
	v_add_f32_e32 v232, v232, v69
	s_waitcnt lgkmcnt(4)
	v_mfma_f32_32x32x16_bf16 v[34:49], v[146:149], v[102:105], v[34:49]
	ds_read_b128 v[146:149], v220 offset:26752
	global_load_dwordx4 v[216:219], v229, s[10:11]
	s_add_u32 s10, s10, 0x80
	s_addc_u32 s11, s11, 0
	v_exp_f32_e32 v72, v72
	v_exp_f32_e32 v73, v73
	v_add_f32_e32 v231, v231, v70
	v_add_f32_e32 v232, v232, v71
	v_mfma_f32_32x32x16_bf16 v[50:65], v[150:153], v[102:105], v[50:65]
	ds_read_b128 v[150:153], v220 offset:33408
	v_add_f32_e32 v231, v231, v72
	v_add_f32_e32 v232, v232, v73
	v_cvt_pk_bf16_f32 v66, v66, v67
	v_cvt_pk_bf16_f32 v67, v68, v69
	v_cvt_pk_bf16_f32 v68, v70, v71
	s_waitcnt lgkmcnt(4)
	v_mfma_f32_32x32x16_bf16 v[34:49], v[154:157], v[106:109], v[34:49]
	ds_read_b128 v[154:157], v220 offset:26784
	v_cvt_pk_bf16_f32 v69, v72, v73
	v_exp_f32_e32 v74, v74
	v_exp_f32_e32 v75, v75
	v_mfma_f32_32x32x16_bf16 v[50:65], v[158:161], v[106:109], v[50:65]
	ds_read_b128 v[158:161], v220 offset:33440
	v_exp_f32_e32 v76, v76
	v_exp_f32_e32 v77, v77
	v_add_f32_e32 v231, v231, v74
	v_add_f32_e32 v232, v232, v75
	s_waitcnt lgkmcnt(4)
	v_mfma_f32_32x32x16_bf16 v[34:49], v[138:141], v[110:113], v[34:49]
	ds_read_b64 v[162:163], v221 offset:8704
	ds_read_b64 v[164:165], v221 offset:8720
	v_exp_f32_e32 v78, v78
	v_exp_f32_e32 v79, v79
	v_add_f32_e32 v231, v231, v76
	v_mfma_f32_32x32x16_bf16 v[50:65], v[142:145], v[110:113], v[50:65]
	ds_read_b64 v[166:167], v221 offset:13056
	ds_read_b64 v[168:169], v221 offset:13072
	v_add_f32_e32 v232, v232, v77
	v_exp_f32_e32 v80, v80
	v_exp_f32_e32 v81, v81
	s_waitcnt lgkmcnt(6)
	v_mfma_f32_32x32x16_bf16 v[34:49], v[146:149], v[114:117], v[34:49]
	ds_read_b64 v[170:171], v221 offset:8736
	ds_read_b64 v[172:173], v221 offset:8752
	v_add_f32_e32 v231, v231, v78
	v_add_f32_e32 v232, v232, v79
	v_add_f32_e32 v231, v231, v80
	v_add_f32_e32 v232, v232, v81
	v_cvt_pk_bf16_f32 v74, v74, v75
	v_cvt_pk_bf16_f32 v75, v76, v77
	v_mfma_f32_32x32x16_bf16 v[50:65], v[150:153], v[114:117], v[50:65]
	ds_read_b64 v[174:175], v221 offset:13088
	ds_read_b64 v[176:177], v221 offset:13104
	v_cvt_pk_bf16_f32 v76, v78, v79
	v_cvt_pk_bf16_f32 v77, v80, v81
	v_exp_f32_e32 v82, v82
	v_exp_f32_e32 v83, v83
	s_waitcnt lgkmcnt(8)
	v_mfma_f32_32x32x16_bf16 v[34:49], v[154:157], v[118:121], v[34:49]
	ds_read_b64 v[180:181], v221 offset:8768
	ds_read_b64 v[182:183], v221 offset:8784
	v_exp_f32_e32 v84, v84
	v_exp_f32_e32 v85, v85
	v_mfma_f32_32x32x16_bf16 v[50:65], v[158:161], v[118:121], v[50:65]
	ds_read_b64 v[184:185], v221 offset:13120
	ds_read_b64 v[186:187], v221 offset:13136
	v_add_f32_e32 v231, v231, v82
	v_add_f32_e32 v232, v232, v83
	v_exp_f32_e32 v86, v86
	v_exp_f32_e32 v87, v87
	s_waitcnt lgkmcnt(8)
	v_mfma_f32_32x32x16_bf16 v[2:17], v[162:165], v[66:69], v[2:17]
	ds_read_b64 v[188:189], v221 offset:8800
	ds_read_b64 v[190:191], v221 offset:8816
	v_add_f32_e32 v231, v231, v84
	v_add_f32_e32 v232, v232, v85
	v_exp_f32_e32 v88, v88
	v_exp_f32_e32 v89, v89
	v_mfma_f32_32x32x16_bf16 v[18:33], v[166:169], v[66:69], v[18:33]
	ds_read_b64 v[192:193], v221 offset:13152
	ds_read_b64 v[194:195], v221 offset:13168
	v_add_f32_e32 v231, v231, v86
	v_add_f32_e32 v232, v232, v87
	v_add_f32_e32 v231, v231, v88
	v_add_f32_e32 v232, v232, v89
	s_waitcnt lgkmcnt(8)
	v_mfma_f32_32x32x16_bf16 v[2:17], v[170:173], v[74:77], v[2:17]
	v_cvt_pk_bf16_f32 v82, v82, v83
	v_cvt_pk_bf16_f32 v83, v84, v85
	v_cvt_pk_bf16_f32 v84, v86, v87
	v_cvt_pk_bf16_f32 v85, v88, v89
	v_exp_f32_e32 v90, v90
	v_mfma_f32_32x32x16_bf16 v[18:33], v[174:177], v[74:77], v[18:33]
	s_waitcnt vmcnt(1)
	ds_write_b128 v222, v[200:203] offset:0
	ds_write_b128 v223, v[204:207] offset:0
	ds_write_b128 v224, v[208:211] offset:0
	ds_write_b64 v225, v[212:213] offset:26112
	ds_write_b64 v225, v[214:215] offset:26120
	v_exp_f32_e32 v91, v91
	v_exp_f32_e32 v92, v92
	v_exp_f32_e32 v93, v93
	s_waitcnt lgkmcnt(9)
	v_mfma_f32_32x32x16_bf16 v[2:17], v[180:183], v[82:85], v[2:17]
	v_add_f32_e32 v231, v231, v90
	v_add_f32_e32 v232, v232, v91
	v_exp_f32_e32 v94, v94
	v_mfma_f32_32x32x16_bf16 v[18:33], v[184:187], v[82:85], v[18:33]
	v_exp_f32_e32 v95, v95
	v_add_f32_e32 v231, v231, v92
	v_add_f32_e32 v232, v232, v93
	v_exp_f32_e32 v96, v96
	v_exp_f32_e32 v97, v97
	v_add_f32_e32 v231, v231, v94
	v_add_f32_e32 v232, v232, v95
	v_add_f32_e32 v231, v231, v96
	v_add_f32_e32 v232, v232, v97
	v_cvt_pk_bf16_f32 v90, v90, v91
	v_cvt_pk_bf16_f32 v91, v92, v93
	v_cvt_pk_bf16_f32 v92, v94, v95
	v_cvt_pk_bf16_f32 v93, v96, v97
	s_waitcnt lgkmcnt(5)
	s_nop 0
	v_mfma_f32_32x32x16_bf16 v[2:17], v[188:191], v[90:93], v[2:17]
	v_mfma_f32_32x32x16_bf16 v[18:33], v[192:195], v[90:93], v[18:33]
	ds_read_b128 v[138:141], v220 offset:39936
	ds_read_b128 v[142:145], v220 offset:46592
	ds_read_b128 v[146:149], v220 offset:39968
	ds_read_b128 v[150:153], v220 offset:46624
	ds_read_b128 v[154:157], v220 offset:40000
	ds_read_b128 v[158:161], v220 offset:46656
	s_waitcnt lgkmcnt(6)
	s_barrier
	v_exp_f32_e32 v34, v34
	v_exp_f32_e32 v35, v35
	v_exp_f32_e32 v36, v36
	s_waitcnt lgkmcnt(4)
	v_mfma_f32_32x32x16_bf16 v[66:81], v[138:141], v[98:101], v[122:137]
	ds_read_b128 v[138:141], v220 offset:40032
	v_exp_f32_e32 v37, v37
	v_add_f32_e32 v231, v231, v34
	v_add_f32_e32 v232, v232, v35
	v_exp_f32_e32 v38, v38
	v_mfma_f32_32x32x16_bf16 v[82:97], v[142:145], v[98:101], v[122:137]
	ds_read_b128 v[142:145], v220 offset:46688
	v_exp_f32_e32 v39, v39
	v_add_f32_e32 v231, v231, v36
	v_add_f32_e32 v232, v232, v37
	s_waitcnt lgkmcnt(4)
	v_mfma_f32_32x32x16_bf16 v[66:81], v[146:149], v[102:105], v[66:81]
	ds_read_b128 v[146:149], v220 offset:40064
	global_load_dwordx4 v[200:203], v226, s[4:5]
	global_load_dwordx4 v[204:207], v227, s[4:5]
	global_load_dwordx4 v[208:211], v228, s[4:5]
	s_add_u32 s4, s4, 0x6000
	s_addc_u32 s5, s5, 0
	global_load_dwordx4 v[212:215], v229, s[10:11]
	s_add_u32 s10, s10, 0x80
	s_addc_u32 s11, s11, 0
	v_exp_f32_e32 v40, v40
	v_exp_f32_e32 v41, v41
	v_add_f32_e32 v231, v231, v38
	v_add_f32_e32 v232, v232, v39
	v_mfma_f32_32x32x16_bf16 v[82:97], v[150:153], v[102:105], v[82:97]
	ds_read_b128 v[150:153], v220 offset:46720
	v_add_f32_e32 v231, v231, v40
	v_add_f32_e32 v232, v232, v41
	v_cvt_pk_bf16_f32 v34, v34, v35
	v_cvt_pk_bf16_f32 v35, v36, v37
	v_cvt_pk_bf16_f32 v36, v38, v39
	s_waitcnt lgkmcnt(4)
	v_mfma_f32_32x32x16_bf16 v[66:81], v[154:157], v[106:109], v[66:81]
	ds_read_b128 v[154:157], v220 offset:40096
	v_cvt_pk_bf16_f32 v37, v40, v41
	v_exp_f32_e32 v42, v42
	v_exp_f32_e32 v43, v43
	v_mfma_f32_32x32x16_bf16 v[82:97], v[158:161], v[106:109], v[82:97]
	ds_read_b128 v[158:161], v220 offset:46752
	v_exp_f32_e32 v44, v44
	v_exp_f32_e32 v45, v45
	v_add_f32_e32 v231, v231, v42
	v_add_f32_e32 v232, v232, v43
	s_waitcnt lgkmcnt(4)
	v_mfma_f32_32x32x16_bf16 v[66:81], v[138:141], v[110:113], v[66:81]
	ds_read_b64 v[162:163], v221 offset:17408
	ds_read_b64 v[164:165], v221 offset:17424
	v_exp_f32_e32 v46, v46
	v_exp_f32_e32 v47, v47
	v_add_f32_e32 v231, v231, v44
	v_mfma_f32_32x32x16_bf16 v[82:97], v[142:145], v[110:113], v[82:97]
	ds_read_b64 v[166:167], v221 offset:21760
	ds_read_b64 v[168:169], v221 offset:21776
	v_add_f32_e32 v232, v232, v45
	v_exp_f32_e32 v48, v48
	v_exp_f32_e32 v49, v49
	s_waitcnt lgkmcnt(6)
	v_mfma_f32_32x32x16_bf16 v[66:81], v[146:149], v[114:117], v[66:81]
	ds_read_b64 v[170:171], v221 offset:17440
	ds_read_b64 v[172:173], v221 offset:17456
	v_add_f32_e32 v231, v231, v46
	v_add_f32_e32 v232, v232, v47
	v_add_f32_e32 v231, v231, v48
	v_add_f32_e32 v232, v232, v49
	v_cvt_pk_bf16_f32 v42, v42, v43
	v_cvt_pk_bf16_f32 v43, v44, v45
	v_mfma_f32_32x32x16_bf16 v[82:97], v[150:153], v[114:117], v[82:97]
	ds_read_b64 v[174:175], v221 offset:21792
	ds_read_b64 v[176:177], v221 offset:21808
	v_cvt_pk_bf16_f32 v44, v46, v47
	v_cvt_pk_bf16_f32 v45, v48, v49
	v_exp_f32_e32 v50, v50
	v_exp_f32_e32 v51, v51
	s_waitcnt lgkmcnt(8)
	v_mfma_f32_32x32x16_bf16 v[66:81], v[154:157], v[118:121], v[66:81]
	ds_read_b64 v[180:181], v221 offset:17472
	ds_read_b64 v[182:183], v221 offset:17488
	v_exp_f32_e32 v52, v52
	v_exp_f32_e32 v53, v53
	v_mfma_f32_32x32x16_bf16 v[82:97], v[158:161], v[118:121], v[82:97]
	ds_read_b64 v[184:185], v221 offset:21824
	ds_read_b64 v[186:187], v221 offset:21840
	v_add_f32_e32 v231, v231, v50
	v_add_f32_e32 v232, v232, v51
	v_exp_f32_e32 v54, v54
	v_exp_f32_e32 v55, v55
	s_waitcnt lgkmcnt(8)
	v_mfma_f32_32x32x16_bf16 v[2:17], v[162:165], v[34:37], v[2:17]
	ds_read_b64 v[188:189], v221 offset:17504
	ds_read_b64 v[190:191], v221 offset:17520
	v_add_f32_e32 v231, v231, v52
	v_add_f32_e32 v232, v232, v53
	v_exp_f32_e32 v56, v56
	v_exp_f32_e32 v57, v57
	v_mfma_f32_32x32x16_bf16 v[18:33], v[166:169], v[34:37], v[18:33]
	ds_read_b64 v[192:193], v221 offset:21856
	ds_read_b64 v[194:195], v221 offset:21872
	v_add_f32_e32 v231, v231, v54
	v_add_f32_e32 v232, v232, v55
	v_add_f32_e32 v231, v231, v56
	v_add_f32_e32 v232, v232, v57
	s_waitcnt lgkmcnt(8)
	v_mfma_f32_32x32x16_bf16 v[2:17], v[170:173], v[42:45], v[2:17]
	v_cvt_pk_bf16_f32 v50, v50, v51
	v_cvt_pk_bf16_f32 v51, v52, v53
	v_cvt_pk_bf16_f32 v52, v54, v55
	v_cvt_pk_bf16_f32 v53, v56, v57
	v_exp_f32_e32 v58, v58
	v_mfma_f32_32x32x16_bf16 v[18:33], v[174:177], v[42:45], v[18:33]
	s_waitcnt vmcnt(4)
	ds_write_b64 v225, v[216:217] offset:0
	ds_write_b64 v225, v[218:219] offset:8
	v_exp_f32_e32 v59, v59
	v_exp_f32_e32 v60, v60
	v_exp_f32_e32 v61, v61
	s_waitcnt lgkmcnt(6)
	v_mfma_f32_32x32x16_bf16 v[2:17], v[180:183], v[50:53], v[2:17]
	v_add_f32_e32 v231, v231, v58
	v_add_f32_e32 v232, v232, v59
	v_exp_f32_e32 v62, v62
	v_mfma_f32_32x32x16_bf16 v[18:33], v[184:187], v[50:53], v[18:33]
	v_exp_f32_e32 v63, v63
	v_add_f32_e32 v231, v231, v60
	v_add_f32_e32 v232, v232, v61
	v_exp_f32_e32 v64, v64
	v_exp_f32_e32 v65, v65
	v_add_f32_e32 v231, v231, v62
	v_add_f32_e32 v232, v232, v63
	v_add_f32_e32 v231, v231, v64
	v_add_f32_e32 v232, v232, v65
	v_cvt_pk_bf16_f32 v58, v58, v59
	v_cvt_pk_bf16_f32 v59, v60, v61
	v_cvt_pk_bf16_f32 v60, v62, v63
	v_cvt_pk_bf16_f32 v61, v64, v65
	s_waitcnt lgkmcnt(2)
	s_nop 0
	v_mfma_f32_32x32x16_bf16 v[2:17], v[188:191], v[58:61], v[2:17]
	v_mfma_f32_32x32x16_bf16 v[18:33], v[192:195], v[58:61], v[18:33]
	ds_read_b128 v[138:141], v220 offset:0
	ds_read_b128 v[142:145], v220 offset:6656
	ds_read_b128 v[146:149], v220 offset:32
	ds_read_b128 v[150:153], v220 offset:6688
	ds_read_b128 v[154:157], v220 offset:64
	ds_read_b128 v[158:161], v220 offset:6720
	s_waitcnt lgkmcnt(6)
	s_barrier
	v_exp_f32_e32 v66, v66
	v_exp_f32_e32 v67, v67
	v_exp_f32_e32 v68, v68
	s_waitcnt lgkmcnt(4)
	v_mfma_f32_32x32x16_bf16 v[34:49], v[138:141], v[98:101], v[122:137]
	ds_read_b128 v[138:141], v220 offset:96
	v_exp_f32_e32 v69, v69
	v_add_f32_e32 v231, v231, v66
	v_add_f32_e32 v232, v232, v67
	v_exp_f32_e32 v70, v70
	v_mfma_f32_32x32x16_bf16 v[50:65], v[142:145], v[98:101], v[122:137]
	ds_read_b128 v[142:145], v220 offset:6752
	v_exp_f32_e32 v71, v71
	v_add_f32_e32 v231, v231, v68
	v_add_f32_e32 v232, v232, v69
	s_waitcnt lgkmcnt(4)
	v_mfma_f32_32x32x16_bf16 v[34:49], v[146:149], v[102:105], v[34:49]
	ds_read_b128 v[146:149], v220 offset:128
	global_load_dwordx4 v[216:219], v229, s[10:11]
	s_add_u32 s10, s10, 0x80
	s_addc_u32 s11, s11, 0
	v_exp_f32_e32 v72, v72
	v_exp_f32_e32 v73, v73
	v_add_f32_e32 v231, v231, v70
	v_add_f32_e32 v232, v232, v71
	v_mfma_f32_32x32x16_bf16 v[50:65], v[150:153], v[102:105], v[50:65]
	ds_read_b128 v[150:153], v220 offset:6784
	v_add_f32_e32 v231, v231, v72
	v_add_f32_e32 v232, v232, v73
	v_cvt_pk_bf16_f32 v66, v66, v67
	v_cvt_pk_bf16_f32 v67, v68, v69
	v_cvt_pk_bf16_f32 v68, v70, v71
	s_waitcnt lgkmcnt(4)
	v_mfma_f32_32x32x16_bf16 v[34:49], v[154:157], v[106:109], v[34:49]
	ds_read_b128 v[154:157], v220 offset:160
	v_cvt_pk_bf16_f32 v69, v72, v73
	v_exp_f32_e32 v74, v74
	v_exp_f32_e32 v75, v75
	v_mfma_f32_32x32x16_bf16 v[50:65], v[158:161], v[106:109], v[50:65]
	ds_read_b128 v[158:161], v220 offset:6816
	v_exp_f32_e32 v76, v76
	v_exp_f32_e32 v77, v77
	v_add_f32_e32 v231, v231, v74
	v_add_f32_e32 v232, v232, v75
	s_waitcnt lgkmcnt(4)
	v_mfma_f32_32x32x16_bf16 v[34:49], v[138:141], v[110:113], v[34:49]
	ds_read_b64 v[162:163], v221 offset:26112
	ds_read_b64 v[164:165], v221 offset:26128
	v_exp_f32_e32 v78, v78
	v_exp_f32_e32 v79, v79
	v_add_f32_e32 v231, v231, v76
	v_mfma_f32_32x32x16_bf16 v[50:65], v[142:145], v[110:113], v[50:65]
	ds_read_b64 v[166:167], v221 offset:30464
	ds_read_b64 v[168:169], v221 offset:30480
	v_add_f32_e32 v232, v232, v77
	v_exp_f32_e32 v80, v80
	v_exp_f32_e32 v81, v81
	s_waitcnt lgkmcnt(6)
	v_mfma_f32_32x32x16_bf16 v[34:49], v[146:149], v[114:117], v[34:49]
	ds_read_b64 v[170:171], v221 offset:26144
	ds_read_b64 v[172:173], v221 offset:26160
	v_add_f32_e32 v231, v231, v78
	v_add_f32_e32 v232, v232, v79
	v_add_f32_e32 v231, v231, v80
	v_add_f32_e32 v232, v232, v81
	v_cvt_pk_bf16_f32 v74, v74, v75
	v_cvt_pk_bf16_f32 v75, v76, v77
	v_mfma_f32_32x32x16_bf16 v[50:65], v[150:153], v[114:117], v[50:65]
	ds_read_b64 v[174:175], v221 offset:30496
	ds_read_b64 v[176:177], v221 offset:30512
	v_cvt_pk_bf16_f32 v76, v78, v79
	v_cvt_pk_bf16_f32 v77, v80, v81
	v_exp_f32_e32 v82, v82
	v_exp_f32_e32 v83, v83
	s_waitcnt lgkmcnt(8)
	v_mfma_f32_32x32x16_bf16 v[34:49], v[154:157], v[118:121], v[34:49]
	ds_read_b64 v[180:181], v221 offset:26176
	ds_read_b64 v[182:183], v221 offset:26192
	v_exp_f32_e32 v84, v84
	v_exp_f32_e32 v85, v85
	v_mfma_f32_32x32x16_bf16 v[50:65], v[158:161], v[118:121], v[50:65]
	ds_read_b64 v[184:185], v221 offset:30528
	ds_read_b64 v[186:187], v221 offset:30544
	v_add_f32_e32 v231, v231, v82
	v_add_f32_e32 v232, v232, v83
	v_exp_f32_e32 v86, v86
	v_exp_f32_e32 v87, v87
	s_waitcnt lgkmcnt(8)
	v_mfma_f32_32x32x16_bf16 v[2:17], v[162:165], v[66:69], v[2:17]
	ds_read_b64 v[188:189], v221 offset:26208
	ds_read_b64 v[190:191], v221 offset:26224
	v_add_f32_e32 v231, v231, v84
	v_add_f32_e32 v232, v232, v85
	v_exp_f32_e32 v88, v88
	v_exp_f32_e32 v89, v89
	v_mfma_f32_32x32x16_bf16 v[18:33], v[166:169], v[66:69], v[18:33]
	ds_read_b64 v[192:193], v221 offset:30560
	ds_read_b64 v[194:195], v221 offset:30576
	v_add_f32_e32 v231, v231, v86
	v_add_f32_e32 v232, v232, v87
	v_add_f32_e32 v231, v231, v88
	v_add_f32_e32 v232, v232, v89
	s_waitcnt lgkmcnt(8)
	v_mfma_f32_32x32x16_bf16 v[2:17], v[170:173], v[74:77], v[2:17]
	v_cvt_pk_bf16_f32 v82, v82, v83
	v_cvt_pk_bf16_f32 v83, v84, v85
	v_cvt_pk_bf16_f32 v84, v86, v87
	v_cvt_pk_bf16_f32 v85, v88, v89
	v_exp_f32_e32 v90, v90
	v_mfma_f32_32x32x16_bf16 v[18:33], v[174:177], v[74:77], v[18:33]
	s_waitcnt vmcnt(1)
	ds_write_b128 v222, v[200:203] offset:26624
	ds_write_b128 v223, v[204:207] offset:26624
	ds_write_b128 v224, v[208:211] offset:26624
	ds_write_b64 v225, v[212:213] offset:8704
	ds_write_b64 v225, v[214:215] offset:8712
	v_exp_f32_e32 v91, v91
	v_exp_f32_e32 v92, v92
	v_exp_f32_e32 v93, v93
	s_waitcnt lgkmcnt(9)
	v_mfma_f32_32x32x16_bf16 v[2:17], v[180:183], v[82:85], v[2:17]
	v_add_f32_e32 v231, v231, v90
	v_add_f32_e32 v232, v232, v91
	v_exp_f32_e32 v94, v94
	v_mfma_f32_32x32x16_bf16 v[18:33], v[184:187], v[82:85], v[18:33]
	v_exp_f32_e32 v95, v95
	v_add_f32_e32 v231, v231, v92
	v_add_f32_e32 v232, v232, v93
	v_exp_f32_e32 v96, v96
	v_exp_f32_e32 v97, v97
	v_add_f32_e32 v231, v231, v94
	v_add_f32_e32 v232, v232, v95
	v_add_f32_e32 v231, v231, v96
	v_add_f32_e32 v232, v232, v97
	v_cvt_pk_bf16_f32 v90, v90, v91
	v_cvt_pk_bf16_f32 v91, v92, v93
	v_cvt_pk_bf16_f32 v92, v94, v95
	v_cvt_pk_bf16_f32 v93, v96, v97
	s_waitcnt lgkmcnt(5)
	s_nop 0
	v_mfma_f32_32x32x16_bf16 v[2:17], v[188:191], v[90:93], v[2:17]
	v_mfma_f32_32x32x16_bf16 v[18:33], v[192:195], v[90:93], v[18:33]
	ds_read_b128 v[138:141], v220 offset:13312
	ds_read_b128 v[142:145], v220 offset:19968
	ds_read_b128 v[146:149], v220 offset:13344
	ds_read_b128 v[150:153], v220 offset:20000
	ds_read_b128 v[154:157], v220 offset:13376
	ds_read_b128 v[158:161], v220 offset:20032
	s_waitcnt lgkmcnt(6)
	s_barrier
	s_add_i32 s16, s16, -1
	s_cmp_lg_u32 s16, 0
	s_cbranch_scc1 .Lmla_loop
	v_exp_f32_e32 v34, v34
	v_exp_f32_e32 v35, v35
	v_exp_f32_e32 v36, v36
	s_waitcnt lgkmcnt(4)
	v_mfma_f32_32x32x16_bf16 v[66:81], v[138:141], v[98:101], v[122:137]
	ds_read_b128 v[138:141], v220 offset:13408
	v_exp_f32_e32 v37, v37
	v_add_f32_e32 v231, v231, v34
	v_add_f32_e32 v232, v232, v35
	v_exp_f32_e32 v38, v38
	v_mfma_f32_32x32x16_bf16 v[82:97], v[142:145], v[98:101], v[122:137]
	ds_read_b128 v[142:145], v220 offset:20064
	v_exp_f32_e32 v39, v39
	v_add_f32_e32 v231, v231, v36
	v_add_f32_e32 v232, v232, v37
	s_waitcnt lgkmcnt(4)
	v_mfma_f32_32x32x16_bf16 v[66:81], v[146:149], v[102:105], v[66:81]
	ds_read_b128 v[146:149], v220 offset:13440
	global_load_dwordx4 v[212:215], v229, s[10:11]
	s_add_u32 s10, s10, 0x80
	s_addc_u32 s11, s11, 0
	v_exp_f32_e32 v40, v40
	v_exp_f32_e32 v41, v41
	v_add_f32_e32 v231, v231, v38
	v_add_f32_e32 v232, v232, v39
	v_mfma_f32_32x32x16_bf16 v[82:97], v[150:153], v[102:105], v[82:97]
	ds_read_b128 v[150:153], v220 offset:20096
	v_add_f32_e32 v231, v231, v40
	v_add_f32_e32 v232, v232, v41
	v_cvt_pk_bf16_f32 v34, v34, v35
	v_cvt_pk_bf16_f32 v35, v36, v37
	v_cvt_pk_bf16_f32 v36, v38, v39
	s_waitcnt lgkmcnt(4)
	v_mfma_f32_32x32x16_bf16 v[66:81], v[154:157], v[106:109], v[66:81]
	ds_read_b128 v[154:157], v220 offset:13472
	v_cvt_pk_bf16_f32 v37, v40, v41
	v_exp_f32_e32 v42, v42
	v_exp_f32_e32 v43, v43
	v_mfma_f32_32x32x16_bf16 v[82:97], v[158:161], v[106:109], v[82:97]
	ds_read_b128 v[158:161], v220 offset:20128
	v_exp_f32_e32 v44, v44
	v_exp_f32_e32 v45, v45
	v_add_f32_e32 v231, v231, v42
	v_add_f32_e32 v232, v232, v43
	s_waitcnt lgkmcnt(4)
	v_mfma_f32_32x32x16_bf16 v[66:81], v[138:141], v[110:113], v[66:81]
	ds_read_b64 v[162:163], v221 offset:0
	ds_read_b64 v[164:165], v221 offset:16
	v_exp_f32_e32 v46, v46
	v_exp_f32_e32 v47, v47
	v_add_f32_e32 v231, v231, v44
	v_mfma_f32_32x32x16_bf16 v[82:97], v[142:145], v[110:113], v[82:97]
	ds_read_b64 v[166:167], v221 offset:4352
	ds_read_b64 v[168:169], v221 offset:4368
	v_add_f32_e32 v232, v232, v45
	v_exp_f32_e32 v48, v48
	v_exp_f32_e32 v49, v49
	s_waitcnt lgkmcnt(6)
	v_mfma_f32_32x32x16_bf16 v[66:81], v[146:149], v[114:117], v[66:81]
	ds_read_b64 v[170:171], v221 offset:32
	ds_read_b64 v[172:173], v221 offset:48
	v_add_f32_e32 v231, v231, v46
	v_add_f32_e32 v232, v232, v47
	v_add_f32_e32 v231, v231, v48
	v_add_f32_e32 v232, v232, v49
	v_cvt_pk_bf16_f32 v42, v42, v43
	v_cvt_pk_bf16_f32 v43, v44, v45
	v_mfma_f32_32x32x16_bf16 v[82:97], v[150:153], v[114:117], v[82:97]
	ds_read_b64 v[174:175], v221 offset:4384
	ds_read_b64 v[176:177], v221 offset:4400
	v_cvt_pk_bf16_f32 v44, v46, v47
	v_cvt_pk_bf16_f32 v45, v48, v49
	v_exp_f32_e32 v50, v50
	v_exp_f32_e32 v51, v51
	s_waitcnt lgkmcnt(8)
	v_mfma_f32_32x32x16_bf16 v[66:81], v[154:157], v[118:121], v[66:81]
	ds_read_b64 v[180:181], v221 offset:64
	ds_read_b64 v[182:183], v221 offset:80
	v_exp_f32_e32 v52, v52
	v_exp_f32_e32 v53, v53
	v_mfma_f32_32x32x16_bf16 v[82:97], v[158:161], v[118:121], v[82:97]
	ds_read_b64 v[184:185], v221 offset:4416
	ds_read_b64 v[186:187], v221 offset:4432
	v_add_f32_e32 v231, v231, v50
	v_add_f32_e32 v232, v232, v51
	v_exp_f32_e32 v54, v54
	v_exp_f32_e32 v55, v55
	s_waitcnt lgkmcnt(8)
	v_mfma_f32_32x32x16_bf16 v[2:17], v[162:165], v[34:37], v[2:17]
	ds_read_b64 v[188:189], v221 offset:96
	ds_read_b64 v[190:191], v221 offset:112
	v_add_f32_e32 v231, v231, v52
	v_add_f32_e32 v232, v232, v53
	v_exp_f32_e32 v56, v56
	v_exp_f32_e32 v57, v57
	v_mfma_f32_32x32x16_bf16 v[18:33], v[166:169], v[34:37], v[18:33]
	ds_read_b64 v[192:193], v221 offset:4448
	ds_read_b64 v[194:195], v221 offset:4464
	v_add_f32_e32 v231, v231, v54
	v_add_f32_e32 v232, v232, v55
	v_add_f32_e32 v231, v231, v56
	v_add_f32_e32 v232, v232, v57
	s_waitcnt lgkmcnt(8)
	v_mfma_f32_32x32x16_bf16 v[2:17], v[170:173], v[42:45], v[2:17]
	v_cvt_pk_bf16_f32 v50, v50, v51
	v_cvt_pk_bf16_f32 v51, v52, v53
	v_cvt_pk_bf16_f32 v52, v54, v55
	v_cvt_pk_bf16_f32 v53, v56, v57
	v_exp_f32_e32 v58, v58
	v_mfma_f32_32x32x16_bf16 v[18:33], v[174:177], v[42:45], v[18:33]
	s_waitcnt vmcnt(1)
	ds_write_b64 v225, v[216:217] offset:17408
	ds_write_b64 v225, v[218:219] offset:17416
	v_exp_f32_e32 v59, v59
	v_exp_f32_e32 v60, v60
	v_exp_f32_e32 v61, v61
	s_waitcnt lgkmcnt(6)
	v_mfma_f32_32x32x16_bf16 v[2:17], v[180:183], v[50:53], v[2:17]
	v_add_f32_e32 v231, v231, v58
	v_add_f32_e32 v232, v232, v59
	v_exp_f32_e32 v62, v62
	v_mfma_f32_32x32x16_bf16 v[18:33], v[184:187], v[50:53], v[18:33]
	v_exp_f32_e32 v63, v63
	v_add_f32_e32 v231, v231, v60
	v_add_f32_e32 v232, v232, v61
	v_exp_f32_e32 v64, v64
	v_exp_f32_e32 v65, v65
	v_add_f32_e32 v231, v231, v62
	v_add_f32_e32 v232, v232, v63
	v_add_f32_e32 v231, v231, v64
	v_add_f32_e32 v232, v232, v65
	v_cvt_pk_bf16_f32 v58, v58, v59
	v_cvt_pk_bf16_f32 v59, v60, v61
	v_cvt_pk_bf16_f32 v60, v62, v63
	v_cvt_pk_bf16_f32 v61, v64, v65
	s_waitcnt lgkmcnt(2)
	s_nop 0
	v_mfma_f32_32x32x16_bf16 v[2:17], v[188:191], v[58:61], v[2:17]
	v_mfma_f32_32x32x16_bf16 v[18:33], v[192:195], v[58:61], v[18:33]
	ds_read_b128 v[138:141], v220 offset:26624
	ds_read_b128 v[142:145], v220 offset:33280
	ds_read_b128 v[146:149], v220 offset:26656
	ds_read_b128 v[150:153], v220 offset:33312
	ds_read_b128 v[154:157], v220 offset:26688
	ds_read_b128 v[158:161], v220 offset:33344
	s_waitcnt lgkmcnt(6)
	s_barrier
	v_exp_f32_e32 v66, v66
	v_exp_f32_e32 v67, v67
	v_exp_f32_e32 v68, v68
	s_waitcnt lgkmcnt(4)
	v_mfma_f32_32x32x16_bf16 v[34:49], v[138:141], v[98:101], v[122:137]
	ds_read_b128 v[138:141], v220 offset:26720
	v_exp_f32_e32 v69, v69
	v_add_f32_e32 v231, v231, v66
	v_add_f32_e32 v232, v232, v67
	v_exp_f32_e32 v70, v70
	v_mfma_f32_32x32x16_bf16 v[50:65], v[142:145], v[98:101], v[122:137]
	ds_read_b128 v[142:145], v220 offset:33376
	v_exp_f32_e32 v71, v71
	v_add_f32_e32 v231, v231, v68
	v_add_f32_e32 v232, v232, v69
	s_waitcnt lgkmcnt(4)
	v_mfma_f32_32x32x16_bf16 v[34:49], v[146:149], v[102:105], v[34:49]
	ds_read_b128 v[146:149], v220 offset:26752
	v_exp_f32_e32 v72, v72
	v_exp_f32_e32 v73, v73
	v_add_f32_e32 v231, v231, v70
	v_add_f32_e32 v232, v232, v71
	v_mfma_f32_32x32x16_bf16 v[50:65], v[150:153], v[102:105], v[50:65]
	ds_read_b128 v[150:153], v220 offset:33408
	v_add_f32_e32 v231, v231, v72
	v_add_f32_e32 v232, v232, v73
	v_cvt_pk_bf16_f32 v66, v66, v67
	v_cvt_pk_bf16_f32 v67, v68, v69
	v_cvt_pk_bf16_f32 v68, v70, v71
	s_waitcnt lgkmcnt(4)
	v_mfma_f32_32x32x16_bf16 v[34:49], v[154:157], v[106:109], v[34:49]
	ds_read_b128 v[154:157], v220 offset:26784
	v_cvt_pk_bf16_f32 v69, v72, v73
	v_exp_f32_e32 v74, v74
	v_exp_f32_e32 v75, v75
	v_mfma_f32_32x32x16_bf16 v[50:65], v[158:161], v[106:109], v[50:65]
	ds_read_b128 v[158:161], v220 offset:33440
	v_exp_f32_e32 v76, v76
	v_exp_f32_e32 v77, v77
	v_add_f32_e32 v231, v231, v74
	v_add_f32_e32 v232, v232, v75
	s_waitcnt lgkmcnt(4)
	v_mfma_f32_32x32x16_bf16 v[34:49], v[138:141], v[110:113], v[34:49]
	ds_read_b64 v[162:163], v221 offset:8704
	ds_read_b64 v[164:165], v221 offset:8720
	v_exp_f32_e32 v78, v78
	v_exp_f32_e32 v79, v79
	v_add_f32_e32 v231, v231, v76
	v_mfma_f32_32x32x16_bf16 v[50:65], v[142:145], v[110:113], v[50:65]
	ds_read_b64 v[166:167], v221 offset:13056
	ds_read_b64 v[168:169], v221 offset:13072
	v_add_f32_e32 v232, v232, v77
	v_exp_f32_e32 v80, v80
	v_exp_f32_e32 v81, v81
	s_waitcnt lgkmcnt(6)
	v_mfma_f32_32x32x16_bf16 v[34:49], v[146:149], v[114:117], v[34:49]
	ds_read_b64 v[170:171], v221 offset:8736
	ds_read_b64 v[172:173], v221 offset:8752
	v_add_f32_e32 v231, v231, v78
	v_add_f32_e32 v232, v232, v79
	v_add_f32_e32 v231, v231, v80
	v_add_f32_e32 v232, v232, v81
	v_cvt_pk_bf16_f32 v74, v74, v75
	v_cvt_pk_bf16_f32 v75, v76, v77
	v_mfma_f32_32x32x16_bf16 v[50:65], v[150:153], v[114:117], v[50:65]
	ds_read_b64 v[174:175], v221 offset:13088
	ds_read_b64 v[176:177], v221 offset:13104
	v_cvt_pk_bf16_f32 v76, v78, v79
	v_cvt_pk_bf16_f32 v77, v80, v81
	v_exp_f32_e32 v82, v82
	v_exp_f32_e32 v83, v83
	s_waitcnt lgkmcnt(8)
	v_mfma_f32_32x32x16_bf16 v[34:49], v[154:157], v[118:121], v[34:49]
	ds_read_b64 v[180:181], v221 offset:8768
	ds_read_b64 v[182:183], v221 offset:8784
	v_exp_f32_e32 v84, v84
	v_exp_f32_e32 v85, v85
	v_mfma_f32_32x32x16_bf16 v[50:65], v[158:161], v[118:121], v[50:65]
	ds_read_b64 v[184:185], v221 offset:13120
	ds_read_b64 v[186:187], v221 offset:13136
	v_add_f32_e32 v231, v231, v82
	v_add_f32_e32 v232, v232, v83
	v_exp_f32_e32 v86, v86
	v_exp_f32_e32 v87, v87
	s_waitcnt lgkmcnt(8)
	v_mfma_f32_32x32x16_bf16 v[2:17], v[162:165], v[66:69], v[2:17]
	ds_read_b64 v[188:189], v221 offset:8800
	ds_read_b64 v[190:191], v221 offset:8816
	v_add_f32_e32 v231, v231, v84
	v_add_f32_e32 v232, v232, v85
	v_exp_f32_e32 v88, v88
	v_exp_f32_e32 v89, v89
	v_mfma_f32_32x32x16_bf16 v[18:33], v[166:169], v[66:69], v[18:33]
	ds_read_b64 v[192:193], v221 offset:13152
	ds_read_b64 v[194:195], v221 offset:13168
	v_add_f32_e32 v231, v231, v86
	v_add_f32_e32 v232, v232, v87
	v_add_f32_e32 v231, v231, v88
	v_add_f32_e32 v232, v232, v89
	s_waitcnt lgkmcnt(8)
	v_mfma_f32_32x32x16_bf16 v[2:17], v[170:173], v[74:77], v[2:17]
	v_cvt_pk_bf16_f32 v82, v82, v83
	v_cvt_pk_bf16_f32 v83, v84, v85
	v_cvt_pk_bf16_f32 v84, v86, v87
	v_cvt_pk_bf16_f32 v85, v88, v89
	v_exp_f32_e32 v90, v90
	v_mfma_f32_32x32x16_bf16 v[18:33], v[174:177], v[74:77], v[18:33]
	s_waitcnt vmcnt(0)
	ds_write_b64 v225, v[212:213] offset:26112
	ds_write_b64 v225, v[214:215] offset:26120
	v_exp_f32_e32 v91, v91
	v_exp_f32_e32 v92, v92
	v_exp_f32_e32 v93, v93
	s_waitcnt lgkmcnt(6)
	v_mfma_f32_32x32x16_bf16 v[2:17], v[180:183], v[82:85], v[2:17]
	v_add_f32_e32 v231, v231, v90
	v_add_f32_e32 v232, v232, v91
	v_exp_f32_e32 v94, v94
	v_mfma_f32_32x32x16_bf16 v[18:33], v[184:187], v[82:85], v[18:33]
	v_exp_f32_e32 v95, v95
	v_add_f32_e32 v231, v231, v92
	v_add_f32_e32 v232, v232, v93
	v_exp_f32_e32 v96, v96
	v_exp_f32_e32 v97, v97
	v_add_f32_e32 v231, v231, v94
	v_add_f32_e32 v232, v232, v95
	v_add_f32_e32 v231, v231, v96
	v_add_f32_e32 v232, v232, v97
	v_cvt_pk_bf16_f32 v90, v90, v91
	v_cvt_pk_bf16_f32 v91, v92, v93
	v_cvt_pk_bf16_f32 v92, v94, v95
	v_cvt_pk_bf16_f32 v93, v96, v97
	s_waitcnt lgkmcnt(2)
	s_nop 0
	v_mfma_f32_32x32x16_bf16 v[2:17], v[188:191], v[90:93], v[2:17]
	v_mfma_f32_32x32x16_bf16 v[18:33], v[192:195], v[90:93], v[18:33]
	ds_read_b128 v[138:141], v220 offset:39936
	ds_read_b128 v[142:145], v220 offset:46592
	ds_read_b128 v[146:149], v220 offset:39968
	ds_read_b128 v[150:153], v220 offset:46624
	ds_read_b128 v[154:157], v220 offset:40000
	ds_read_b128 v[158:161], v220 offset:46656
	s_waitcnt lgkmcnt(6)
	s_barrier
	global_load_dwordx2 v[200:201], v236, s[14:15] offset:0
	global_load_dwordx2 v[202:203], v236, s[14:15] offset:16
	global_load_dwordx2 v[204:205], v236, s[14:15] offset:32
	global_load_dwordx2 v[206:207], v236, s[14:15] offset:48
	global_load_dwordx2 v[208:209], v236, s[14:15] offset:64
	global_load_dwordx2 v[210:211], v236, s[14:15] offset:80
	global_load_dwordx2 v[212:213], v236, s[14:15] offset:96
	global_load_dwordx2 v[214:215], v236, s[14:15] offset:112
	v_exp_f32_e32 v34, v34
	v_exp_f32_e32 v35, v35
	v_exp_f32_e32 v36, v36
	s_waitcnt lgkmcnt(4)
	v_mfma_f32_32x32x16_bf16 v[66:81], v[138:141], v[98:101], v[122:137]
	ds_read_b128 v[138:141], v220 offset:40032
	v_exp_f32_e32 v37, v37
	v_add_f32_e32 v231, v231, v34
	v_add_f32_e32 v232, v232, v35
	v_exp_f32_e32 v38, v38
	v_mfma_f32_32x32x16_bf16 v[82:97], v[142:145], v[98:101], v[122:137]
	ds_read_b128 v[142:145], v220 offset:46688
	v_exp_f32_e32 v39, v39
	v_add_f32_e32 v231, v231, v36
	v_add_f32_e32 v232, v232, v37
	s_waitcnt lgkmcnt(4)
	v_mfma_f32_32x32x16_bf16 v[66:81], v[146:149], v[102:105], v[66:81]
	ds_read_b128 v[146:149], v220 offset:40064
	v_exp_f32_e32 v40, v40
	v_exp_f32_e32 v41, v41
	v_add_f32_e32 v231, v231, v38
	v_add_f32_e32 v232, v232, v39
	v_mfma_f32_32x32x16_bf16 v[82:97], v[150:153], v[102:105], v[82:97]
	ds_read_b128 v[150:153], v220 offset:46720
	v_add_f32_e32 v231, v231, v40
	v_add_f32_e32 v232, v232, v41
	v_cvt_pk_bf16_f32 v34, v34, v35
	v_cvt_pk_bf16_f32 v35, v36, v37
	v_cvt_pk_bf16_f32 v36, v38, v39
	s_waitcnt lgkmcnt(4)
	v_mfma_f32_32x32x16_bf16 v[66:81], v[154:157], v[106:109], v[66:81]
	ds_read_b128 v[154:157], v220 offset:40096
	v_cvt_pk_bf16_f32 v37, v40, v41
	v_exp_f32_e32 v42, v42
	v_exp_f32_e32 v43, v43
	v_mfma_f32_32x32x16_bf16 v[82:97], v[158:161], v[106:109], v[82:97]
	ds_read_b128 v[158:161], v220 offset:46752
	v_exp_f32_e32 v44, v44
	v_exp_f32_e32 v45, v45
	v_add_f32_e32 v231, v231, v42
	v_add_f32_e32 v232, v232, v43
	s_waitcnt lgkmcnt(4)
	v_mfma_f32_32x32x16_bf16 v[66:81], v[138:141], v[110:113], v[66:81]
	ds_read_b64 v[162:163], v221 offset:17408
	ds_read_b64 v[164:165], v221 offset:17424
	v_exp_f32_e32 v46, v46
	v_exp_f32_e32 v47, v47
	v_add_f32_e32 v231, v231, v44
	v_mfma_f32_32x32x16_bf16 v[82:97], v[142:145], v[110:113], v[82:97]
	ds_read_b64 v[166:167], v221 offset:21760
	ds_read_b64 v[168:169], v221 offset:21776
	v_add_f32_e32 v232, v232, v45
	v_exp_f32_e32 v48, v48
	v_exp_f32_e32 v49, v49
	s_waitcnt lgkmcnt(6)
	v_mfma_f32_32x32x16_bf16 v[66:81], v[146:149], v[114:117], v[66:81]
	ds_read_b64 v[170:171], v221 offset:17440
	ds_read_b64 v[172:173], v221 offset:17456
	v_add_f32_e32 v231, v231, v46
	v_add_f32_e32 v232, v232, v47
	v_add_f32_e32 v231, v231, v48
	v_add_f32_e32 v232, v232, v49
	v_cvt_pk_bf16_f32 v42, v42, v43
	v_cvt_pk_bf16_f32 v43, v44, v45
	v_mfma_f32_32x32x16_bf16 v[82:97], v[150:153], v[114:117], v[82:97]
	ds_read_b64 v[174:175], v221 offset:21792
	ds_read_b64 v[176:177], v221 offset:21808
	v_cvt_pk_bf16_f32 v44, v46, v47
	v_cvt_pk_bf16_f32 v45, v48, v49
	v_exp_f32_e32 v50, v50
	v_exp_f32_e32 v51, v51
	s_waitcnt lgkmcnt(8)
	v_mfma_f32_32x32x16_bf16 v[66:81], v[154:157], v[118:121], v[66:81]
	ds_read_b64 v[180:181], v221 offset:17472
	ds_read_b64 v[182:183], v221 offset:17488
	v_exp_f32_e32 v52, v52
	v_exp_f32_e32 v53, v53
	v_mfma_f32_32x32x16_bf16 v[82:97], v[158:161], v[118:121], v[82:97]
	ds_read_b64 v[184:185], v221 offset:21824
	ds_read_b64 v[186:187], v221 offset:21840
	v_add_f32_e32 v231, v231, v50
	v_add_f32_e32 v232, v232, v51
	v_exp_f32_e32 v54, v54
	v_exp_f32_e32 v55, v55
	s_waitcnt lgkmcnt(8)
	v_mfma_f32_32x32x16_bf16 v[2:17], v[162:165], v[34:37], v[2:17]
	ds_read_b64 v[188:189], v221 offset:17504
	ds_read_b64 v[190:191], v221 offset:17520
	v_add_f32_e32 v231, v231, v52
	v_add_f32_e32 v232, v232, v53
	v_exp_f32_e32 v56, v56
	v_exp_f32_e32 v57, v57
	v_mfma_f32_32x32x16_bf16 v[18:33], v[166:169], v[34:37], v[18:33]
	ds_read_b64 v[192:193], v221 offset:21856
	ds_read_b64 v[194:195], v221 offset:21872
	v_add_f32_e32 v231, v231, v54
	v_add_f32_e32 v232, v232, v55
	v_add_f32_e32 v231, v231, v56
	v_add_f32_e32 v232, v232, v57
	s_waitcnt lgkmcnt(8)
	v_mfma_f32_32x32x16_bf16 v[2:17], v[170:173], v[42:45], v[2:17]
	v_cvt_pk_bf16_f32 v50, v50, v51
	v_cvt_pk_bf16_f32 v51, v52, v53
	v_cvt_pk_bf16_f32 v52, v54, v55
	v_cvt_pk_bf16_f32 v53, v56, v57
	v_exp_f32_e32 v58, v58
	v_mfma_f32_32x32x16_bf16 v[18:33], v[174:177], v[42:45], v[18:33]
	v_exp_f32_e32 v59, v59
	v_exp_f32_e32 v60, v60
	v_exp_f32_e32 v61, v61
	s_waitcnt lgkmcnt(4)
	v_mfma_f32_32x32x16_bf16 v[2:17], v[180:183], v[50:53], v[2:17]
	v_add_f32_e32 v231, v231, v58
	v_add_f32_e32 v232, v232, v59
	v_exp_f32_e32 v62, v62
	v_mfma_f32_32x32x16_bf16 v[18:33], v[184:187], v[50:53], v[18:33]
	v_exp_f32_e32 v63, v63
	v_add_f32_e32 v231, v231, v60
	v_add_f32_e32 v232, v232, v61
	v_exp_f32_e32 v64, v64
	v_exp_f32_e32 v65, v65
	v_add_f32_e32 v231, v231, v62
	v_add_f32_e32 v232, v232, v63
	v_add_f32_e32 v231, v231, v64
	v_add_f32_e32 v232, v232, v65
	v_cvt_pk_bf16_f32 v58, v58, v59
	v_cvt_pk_bf16_f32 v59, v60, v61
	v_cvt_pk_bf16_f32 v60, v62, v63
	v_cvt_pk_bf16_f32 v61, v64, v65
	s_waitcnt lgkmcnt(0)
	s_nop 0
	v_mfma_f32_32x32x16_bf16 v[2:17], v[188:191], v[58:61], v[2:17]
	v_mfma_f32_32x32x16_bf16 v[18:33], v[192:195], v[58:61], v[18:33]
	s_waitcnt lgkmcnt(0)
	s_barrier
	s_mov_b64 s[24:25], s[14:15]
	s_add_i32 s2, s2, s88
	s_cmpk_lt_i32 s2, 0x200
	s_cbranch_scc0 .Lmla_nopf
	s_lshr_b32 s17, s2, 4
	s_and_b32 s18, s2, 15
	s_mul_i32 s19, s17, 0xcc000
	s_add_u32 s4, s78, s19
	s_addc_u32 s5, s79, 0
	s_mul_i32 s19, s17, 0x88000
	s_add_u32 s19, s19, 0x1a00000
	s_add_u32 s10, s78, s19
	s_addc_u32 s11, s79, 0
	s_lshl_b32 s19, s17, 12
	s_lshl_b32 s20, s18, 8
	s_add_u32 s19, s19, s20
	s_mul_i32 s19, s19, 0xc0
	s_add_u32 s19, s19, 0x1400000
	s_add_u32 s12, s80, s19
	s_addc_u32 s13, s81, 0
	s_lshr_b32 s19, s17, 3
	s_lshl_b32 s19, s19, 12
	s_add_u32 s19, s19, s20
	s_lshl_b32 s19, s19, 10
	s_and_b32 s21, s17, 7
	s_lshl_b32 s21, s21, 7
	s_add_u32 s19, s19, s21
	s_add_u32 s19, s19, 0x7900000
	s_add_u32 s14, s80, s19
	s_addc_u32 s15, s81, 0
	global_load_dwordx4 v[98:101], v237, s[12:13] offset:0
	global_load_dwordx4 v[102:105], v237, s[12:13] offset:32
	global_load_dwordx4 v[106:109], v237, s[12:13] offset:64
	global_load_dwordx4 v[110:113], v237, s[12:13] offset:96
	global_load_dwordx4 v[114:117], v237, s[12:13] offset:128
	global_load_dwordx4 v[118:121], v237, s[12:13] offset:160
	global_load_dwordx4 v[34:37], v226, s[4:5]
	global_load_dwordx4 v[38:41], v227, s[4:5]
	global_load_dwordx4 v[42:45], v228, s[4:5]
	global_load_dwordx4 v[46:49], v229, s[10:11]
	s_add_u32 s4, s4, 0x6000
	s_addc_u32 s5, s5, 0
	global_load_dwordx4 v[50:53], v226, s[4:5]
	global_load_dwordx4 v[54:57], v227, s[4:5]
	global_load_dwordx4 v[58:61], v228, s[4:5]
	global_load_dwordx4 v[62:65], v229, s[10:11] offset:128
	global_load_dwordx4 v[216:219], v229, s[10:11] offset:256
	s_add_u32 s4, s4, 0x6000
	s_addc_u32 s5, s5, 0
	s_add_u32 s10, s10, 0x180
	s_addc_u32 s11, s11, 0
.Lmla_nopf:
	ds_read_b64 v[162:163], v221 offset:26112
	ds_read_b64 v[164:165], v221 offset:26128
	ds_read_b64 v[166:167], v221 offset:30464
	ds_read_b64 v[168:169], v221 offset:30480
	ds_read_b64 v[170:171], v221 offset:26144
	ds_read_b64 v[172:173], v221 offset:26160
	v_exp_f32_e32 v66, v66
	v_exp_f32_e32 v67, v67
	v_exp_f32_e32 v68, v68
	v_exp_f32_e32 v69, v69
	v_add_f32_e32 v231, v231, v66
	v_add_f32_e32 v232, v232, v67
	v_exp_f32_e32 v70, v70
	v_exp_f32_e32 v71, v71
	v_add_f32_e32 v231, v231, v68
	v_add_f32_e32 v232, v232, v69
	v_exp_f32_e32 v72, v72
	v_exp_f32_e32 v73, v73
	v_add_f32_e32 v231, v231, v70
	v_add_f32_e32 v232, v232, v71
	v_add_f32_e32 v231, v231, v72
	v_add_f32_e32 v232, v232, v73
	v_cvt_pk_bf16_f32 v66, v66, v67
	v_cvt_pk_bf16_f32 v67, v68, v69
	v_cvt_pk_bf16_f32 v68, v70, v71
	v_cvt_pk_bf16_f32 v69, v72, v73
	s_waitcnt lgkmcnt(2)
	s_nop 0
	v_mfma_f32_32x32x16_bf16 v[2:17], v[162:165], v[66:69], v[2:17]
	ds_read_b64 v[174:175], v221 offset:30496
	ds_read_b64 v[176:177], v221 offset:30512
	v_mfma_f32_32x32x16_bf16 v[18:33], v[166:169], v[66:69], v[18:33]
	ds_read_b64 v[180:181], v221 offset:26176
	ds_read_b64 v[182:183], v221 offset:26192
	v_exp_f32_e32 v74, v74
	v_exp_f32_e32 v75, v75
	v_exp_f32_e32 v76, v76
	v_exp_f32_e32 v77, v77
	v_add_f32_e32 v231, v231, v74
	v_add_f32_e32 v232, v232, v75
	v_exp_f32_e32 v78, v78
	v_exp_f32_e32 v79, v79
	v_add_f32_e32 v231, v231, v76
	v_add_f32_e32 v232, v232, v77
	v_exp_f32_e32 v80, v80
	v_exp_f32_e32 v81, v81
	v_add_f32_e32 v231, v231, v78
	v_add_f32_e32 v232, v232, v79
	v_add_f32_e32 v231, v231, v80
	v_add_f32_e32 v232, v232, v81
	v_cvt_pk_bf16_f32 v74, v74, v75
	v_cvt_pk_bf16_f32 v75, v76, v77
	v_cvt_pk_bf16_f32 v76, v78, v79
	v_cvt_pk_bf16_f32 v77, v80, v81
	s_waitcnt lgkmcnt(2)
	s_nop 0
	v_mfma_f32_32x32x16_bf16 v[2:17], v[170:173], v[74:77], v[2:17]
	ds_read_b64 v[184:185], v221 offset:30528
	ds_read_b64 v[186:187], v221 offset:30544
	v_mfma_f32_32x32x16_bf16 v[18:33], v[174:177], v[74:77], v[18:33]
	ds_read_b64 v[188:189], v221 offset:26208
	ds_read_b64 v[190:191], v221 offset:26224
	v_exp_f32_e32 v82, v82
	v_exp_f32_e32 v83, v83
	v_exp_f32_e32 v84, v84
	v_exp_f32_e32 v85, v85
	v_add_f32_e32 v231, v231, v82
	v_add_f32_e32 v232, v232, v83
	v_exp_f32_e32 v86, v86
	v_exp_f32_e32 v87, v87
	v_add_f32_e32 v231, v231, v84
	v_add_f32_e32 v232, v232, v85
	v_exp_f32_e32 v88, v88
	v_exp_f32_e32 v89, v89
	v_add_f32_e32 v231, v231, v86
	v_add_f32_e32 v232, v232, v87
	v_add_f32_e32 v231, v231, v88
	v_add_f32_e32 v232, v232, v89
	v_cvt_pk_bf16_f32 v82, v82, v83
	v_cvt_pk_bf16_f32 v83, v84, v85
	v_cvt_pk_bf16_f32 v84, v86, v87
	v_cvt_pk_bf16_f32 v85, v88, v89
	s_waitcnt lgkmcnt(2)
	s_nop 0
	v_mfma_f32_32x32x16_bf16 v[2:17], v[180:183], v[82:85], v[2:17]
	ds_read_b64 v[192:193], v221 offset:30560
	ds_read_b64 v[194:195], v221 offset:30576
	v_mfma_f32_32x32x16_bf16 v[18:33], v[184:187], v[82:85], v[18:33]
	v_exp_f32_e32 v90, v90
	v_exp_f32_e32 v91, v91
	v_exp_f32_e32 v92, v92
	v_exp_f32_e32 v93, v93
	v_add_f32_e32 v231, v231, v90
	v_add_f32_e32 v232, v232, v91
	v_exp_f32_e32 v94, v94
	v_exp_f32_e32 v95, v95
	v_add_f32_e32 v231, v231, v92
	v_add_f32_e32 v232, v232, v93
	v_exp_f32_e32 v96, v96
	v_exp_f32_e32 v97, v97
	v_add_f32_e32 v231, v231, v94
	v_add_f32_e32 v232, v232, v95
	v_add_f32_e32 v231, v231, v96
	v_add_f32_e32 v232, v232, v97
	v_cvt_pk_bf16_f32 v90, v90, v91
	v_cvt_pk_bf16_f32 v91, v92, v93
	v_cvt_pk_bf16_f32 v92, v94, v95
	v_cvt_pk_bf16_f32 v93, v96, v97
	s_waitcnt lgkmcnt(0)
	s_nop 0
	v_mfma_f32_32x32x16_bf16 v[2:17], v[188:191], v[90:93], v[2:17]
	v_mfma_f32_32x32x16_bf16 v[18:33], v[192:195], v[90:93], v[18:33]
	s_waitcnt lgkmcnt(0)
	s_barrier
	v_add_f32_e32 v231, v231, v232
	v_mov_b32_e32 v235, v231
	s_nop 1
	v_permlane32_swap_b32_e32 v231, v235
	v_add_f32_e32 v234, v231, v235
	v_mov_b32_e32 v233, v234
	v_div_scale_f32 v235, s[22:23], v234, v234, 1.0
	v_rcp_f32_e32 v179, v235
	v_div_scale_f32 v196, vcc, 1.0, v234, 1.0
	v_fma_f32 v197, -v235, v179, 1.0
	v_fmac_f32_e32 v179, v197, v179
	v_mul_f32_e32 v197, v196, v179
	v_fma_f32 v199, -v235, v197, v196
	v_fmac_f32_e32 v197, v199, v179
	v_fma_f32 v235, -v235, v197, v196
	v_div_fmas_f32 v235, v235, v179, v197
	v_div_fixup_f32 v234, v235, v234, 1.0
	s_nop 15
	v_mul_f32_e32 v2, v2, v234
	v_mul_f32_e32 v3, v3, v234
	v_mul_f32_e32 v4, v4, v234
	v_mul_f32_e32 v5, v5, v234
	v_mul_f32_e32 v6, v6, v234
	v_mul_f32_e32 v7, v7, v234
	v_mul_f32_e32 v8, v8, v234
	v_mul_f32_e32 v9, v9, v234
	v_mul_f32_e32 v10, v10, v234
	v_mul_f32_e32 v11, v11, v234
	v_mul_f32_e32 v12, v12, v234
	v_mul_f32_e32 v13, v13, v234
	v_mul_f32_e32 v14, v14, v234
	v_mul_f32_e32 v15, v15, v234
	v_mul_f32_e32 v16, v16, v234
	v_mul_f32_e32 v17, v17, v234
	v_mul_f32_e32 v18, v18, v234
	v_mul_f32_e32 v19, v19, v234
	v_mul_f32_e32 v20, v20, v234
	v_mul_f32_e32 v21, v21, v234
	v_mul_f32_e32 v22, v22, v234
	v_mul_f32_e32 v23, v23, v234
	v_mul_f32_e32 v24, v24, v234
	v_mul_f32_e32 v25, v25, v234
	v_mul_f32_e32 v26, v26, v234
	v_mul_f32_e32 v27, v27, v234
	v_mul_f32_e32 v28, v28, v234
	v_mul_f32_e32 v29, v29, v234
	v_mul_f32_e32 v30, v30, v234
	v_mul_f32_e32 v31, v31, v234
	v_mul_f32_e32 v32, v32, v234
	v_mul_f32_e32 v33, v33, v234
	v_mov_b32_e32 v235, 0
	v_fmac_f32_e32 v235, 0, v2
	v_fmac_f32_e32 v235, 0, v3
	v_fmac_f32_e32 v235, 0, v4
	v_fmac_f32_e32 v235, 0, v5
	v_fmac_f32_e32 v235, 0, v6
	v_fmac_f32_e32 v235, 0, v7
	v_fmac_f32_e32 v235, 0, v8
	v_fmac_f32_e32 v235, 0, v9
	v_fmac_f32_e32 v235, 0, v10
	v_fmac_f32_e32 v235, 0, v11
	v_fmac_f32_e32 v235, 0, v12
	v_fmac_f32_e32 v235, 0, v13
	v_fmac_f32_e32 v235, 0, v14
	v_fmac_f32_e32 v235, 0, v15
	v_fmac_f32_e32 v235, 0, v16
	v_fmac_f32_e32 v235, 0, v17
	v_fmac_f32_e32 v235, 0, v18
	v_fmac_f32_e32 v235, 0, v19
	v_fmac_f32_e32 v235, 0, v20
	v_fmac_f32_e32 v235, 0, v21
	v_fmac_f32_e32 v235, 0, v22
	v_fmac_f32_e32 v235, 0, v23
	v_fmac_f32_e32 v235, 0, v24
	v_fmac_f32_e32 v235, 0, v25
	v_fmac_f32_e32 v235, 0, v26
	v_fmac_f32_e32 v235, 0, v27
	v_fmac_f32_e32 v235, 0, v28
	v_fmac_f32_e32 v235, 0, v29
	v_fmac_f32_e32 v235, 0, v30
	v_fmac_f32_e32 v235, 0, v31
	v_fmac_f32_e32 v235, 0, v32
	v_fmac_f32_e32 v235, 0, v33
	v_fmac_f32_e32 v235, 0, v233
	v_cmp_u_f32_e32 vcc, v235, v235
	s_cmp_lg_u64 vcc, 0
	s_cselect_b32 s26, 1, 0
	v_mov_b32_e32 v179, 0x186a0
	v_mov_b32_e32 v196, s26
	ds_or_b32 v179, v196
	s_waitcnt lgkmcnt(0)
	s_barrier
	ds_read_b32 v196, v179
	s_waitcnt lgkmcnt(0)
	v_readfirstlane_b32 s26, v196
	s_barrier
	v_mov_b32_e32 v196, 0
	ds_write_b32 v179, v196
	s_cmp_lg_u32 s26, 0
	s_cbranch_scc1 .Lmla_redo
	s_cmpk_lt_i32 s2, 0x200
	s_cbranch_scc1 .Lmla_zw15
	s_waitcnt vmcnt(0)
	s_branch .Lmla_zw

.Lmla_redo:
	s_sub_i32 s2, s2, s88
	s_waitcnt vmcnt(0)
	s_lshr_b32 s17, s2, 4
	s_and_b32 s18, s2, 15
	s_mul_i32 s19, s17, 0xcc000
	s_add_u32 s4, s78, s19
	s_addc_u32 s5, s79, 0
	s_mul_i32 s19, s17, 0x88000
	s_add_u32 s19, s19, 0x1a00000
	s_add_u32 s10, s78, s19
	s_addc_u32 s11, s79, 0
	s_lshl_b32 s19, s17, 12
	s_lshl_b32 s20, s18, 8
	s_add_u32 s19, s19, s20
	s_mul_i32 s19, s19, 0xc0
	s_add_u32 s19, s19, 0x1400000
	s_add_u32 s12, s80, s19
	s_addc_u32 s13, s81, 0
	s_lshr_b32 s19, s17, 3
	s_lshl_b32 s19, s19, 12
	s_add_u32 s19, s19, s20
	s_lshl_b32 s19, s19, 10
	s_and_b32 s21, s17, 7
	s_lshl_b32 s21, s21, 7
	s_add_u32 s19, s19, s21
	s_add_u32 s19, s19, 0x7900000
	s_add_u32 s14, s80, s19
	s_addc_u32 s15, s81, 0
	global_load_dwordx4 v[98:101], v237, s[12:13] offset:0
	global_load_dwordx4 v[102:105], v237, s[12:13] offset:32
	global_load_dwordx4 v[106:109], v237, s[12:13] offset:64
	global_load_dwordx4 v[110:113], v237, s[12:13] offset:96
	global_load_dwordx4 v[114:117], v237, s[12:13] offset:128
	global_load_dwordx4 v[118:121], v237, s[12:13] offset:160
	global_load_dwordx4 v[200:203], v226, s[4:5]
	global_load_dwordx4 v[204:207], v227, s[4:5]
	global_load_dwordx4 v[208:211], v228, s[4:5]
	global_load_dwordx4 v[66:69], v229, s[10:11]
	s_add_u32 s4, s4, 0x6000
	s_addc_u32 s5, s5, 0
	global_load_dwordx4 v[70:73], v226, s[4:5]
	global_load_dwordx4 v[74:77], v227, s[4:5]
	global_load_dwordx4 v[78:81], v228, s[4:5]
	global_load_dwordx4 v[82:85], v229, s[10:11] offset:128
	global_load_dwordx4 v[216:219], v229, s[10:11] offset:256
	s_add_u32 s4, s4, 0x6000
	s_addc_u32 s5, s5, 0
	s_add_u32 s10, s10, 0x180
	s_addc_u32 s11, s11, 0
	v_mov_b32_e32 v2, 0
	v_mov_b32_e32 v3, 0
	v_mov_b32_e32 v4, 0
	v_mov_b32_e32 v5, 0
	v_mov_b32_e32 v6, 0
	v_mov_b32_e32 v7, 0
	v_mov_b32_e32 v8, 0
	v_mov_b32_e32 v9, 0
	v_mov_b32_e32 v10, 0
	v_mov_b32_e32 v11, 0
	v_mov_b32_e32 v12, 0
	v_mov_b32_e32 v13, 0
	v_mov_b32_e32 v14, 0
	v_mov_b32_e32 v15, 0
	v_mov_b32_e32 v16, 0
	v_mov_b32_e32 v17, 0
	v_mov_b32_e32 v18, 0
	v_mov_b32_e32 v19, 0
	v_mov_b32_e32 v20, 0
	v_mov_b32_e32 v21, 0
	v_mov_b32_e32 v22, 0
	v_mov_b32_e32 v23, 0
	v_mov_b32_e32 v24, 0
	v_mov_b32_e32 v25, 0
	v_mov_b32_e32 v26, 0
	v_mov_b32_e32 v27, 0
	v_mov_b32_e32 v28, 0
	v_mov_b32_e32 v29, 0
	v_mov_b32_e32 v30, 0
	v_mov_b32_e32 v31, 0
	v_mov_b32_e32 v32, 0
	v_mov_b32_e32 v33, 0
	v_mov_b32_e32 v122, 0
	v_mov_b32_e32 v123, 0
	v_mov_b32_e32 v124, 0
	v_mov_b32_e32 v125, 0
	v_mov_b32_e32 v126, 0
	v_mov_b32_e32 v127, 0
	v_mov_b32_e32 v128, 0
	v_mov_b32_e32 v129, 0
	v_mov_b32_e32 v130, 0
	v_mov_b32_e32 v131, 0
	v_mov_b32_e32 v132, 0
	v_mov_b32_e32 v133, 0
	v_mov_b32_e32 v134, 0
	v_mov_b32_e32 v135, 0
	v_mov_b32_e32 v136, 0
	v_mov_b32_e32 v137, 0
	v_mov_b32_e32 v230, 0
	v_mov_b32_e32 v231, 0
	v_mov_b32_e32 v232, 0
	s_waitcnt vmcnt(5)
	ds_write_b128 v222, v[200:203]
	ds_write_b128 v223, v[204:207]
	ds_write_b128 v224, v[208:211]
	ds_write_b64 v225, v[66:67]
	ds_write_b64 v225, v[68:69] offset:8
	s_waitcnt vmcnt(1)
	ds_write_b128 v222, v[70:73] offset:26624
	ds_write_b128 v223, v[74:77] offset:26624
	ds_write_b128 v224, v[78:81] offset:26624
	ds_write_b64 v225, v[82:83] offset:8704
	ds_write_b64 v225, v[84:85] offset:8712
	s_waitcnt lgkmcnt(0)
	s_barrier
	ds_read_b128 v[138:141], v220 offset:0
	ds_read_b128 v[142:145], v220 offset:6656
	ds_read_b128 v[146:149], v220 offset:32
	ds_read_b128 v[150:153], v220 offset:6688
	ds_read_b128 v[154:157], v220 offset:64
	ds_read_b128 v[158:161], v220 offset:6720
	ds_read_b128 v[66:69], v220 offset:96
	ds_read_b128 v[70:73], v220 offset:6752
	ds_read_b128 v[74:77], v220 offset:128
	ds_read_b128 v[78:81], v220 offset:6784
	ds_read_b128 v[82:85], v220 offset:160
	ds_read_b128 v[86:89], v220 offset:6816
	s_waitcnt lgkmcnt(11)
	v_mfma_f32_32x32x16_bf16 v[34:49], v[138:141], v[98:101], v[122:137]
	s_waitcnt lgkmcnt(10)
	v_mfma_f32_32x32x16_bf16 v[50:65], v[142:145], v[98:101], v[122:137]
	s_waitcnt lgkmcnt(9)
	v_mfma_f32_32x32x16_bf16 v[34:49], v[146:149], v[102:105], v[34:49]
	s_waitcnt lgkmcnt(8)
	v_mfma_f32_32x32x16_bf16 v[50:65], v[150:153], v[102:105], v[50:65]
	s_waitcnt lgkmcnt(7)
	v_mfma_f32_32x32x16_bf16 v[34:49], v[154:157], v[106:109], v[34:49]
	s_waitcnt lgkmcnt(6)
	v_mfma_f32_32x32x16_bf16 v[50:65], v[158:161], v[106:109], v[50:65]
	s_waitcnt lgkmcnt(5)
	v_mfma_f32_32x32x16_bf16 v[34:49], v[66:69], v[110:113], v[34:49]
	s_waitcnt lgkmcnt(4)
	v_mfma_f32_32x32x16_bf16 v[50:65], v[70:73], v[110:113], v[50:65]
	s_waitcnt lgkmcnt(3)
	v_mfma_f32_32x32x16_bf16 v[34:49], v[74:77], v[114:117], v[34:49]
	s_waitcnt lgkmcnt(2)
	v_mfma_f32_32x32x16_bf16 v[50:65], v[78:81], v[114:117], v[50:65]
	s_waitcnt lgkmcnt(1)
	v_mfma_f32_32x32x16_bf16 v[34:49], v[82:85], v[118:121], v[34:49]
	s_waitcnt lgkmcnt(0)
	v_mfma_f32_32x32x16_bf16 v[50:65], v[86:89], v[118:121], v[50:65]
	s_nop 15
	v_max3_f32 v234, v34, v35, v36
	v_max3_f32 v235, v50, v51, v52
	v_max3_f32 v234, v234, v37, v38
	v_max3_f32 v235, v235, v53, v54
	v_max3_f32 v234, v234, v39, v40
	v_max3_f32 v235, v235, v55, v56
	v_max3_f32 v234, v234, v41, v42
	v_max3_f32 v235, v235, v57, v58
	v_max3_f32 v234, v234, v43, v44
	v_max3_f32 v235, v235, v59, v60
	v_max3_f32 v234, v234, v45, v46
	v_max3_f32 v235, v235, v61, v62
	v_max3_f32 v234, v234, v47, v48
	v_max3_f32 v235, v235, v63, v64
	v_max3_f32 v234, v234, v49, v65
	v_max_f32_e32 v234, v234, v235
	v_mov_b32_e32 v235, v234
	s_nop 1
	v_permlane32_swap_b32_e32 v234, v235
	v_max_f32_e32 v233, v234, v235
	s_nop 15
	v_add_f32_e32 v230, v230, v233
	v_sub_f32_e32 v34, v34, v233
	v_sub_f32_e32 v35, v35, v233
	v_sub_f32_e32 v36, v36, v233
	v_sub_f32_e32 v37, v37, v233
	v_sub_f32_e32 v38, v38, v233
	v_sub_f32_e32 v39, v39, v233
	v_sub_f32_e32 v40, v40, v233
	v_sub_f32_e32 v41, v41, v233
	v_sub_f32_e32 v42, v42, v233
	v_sub_f32_e32 v43, v43, v233
	v_sub_f32_e32 v44, v44, v233
	v_sub_f32_e32 v45, v45, v233
	v_sub_f32_e32 v46, v46, v233
	v_sub_f32_e32 v47, v47, v233
	v_sub_f32_e32 v48, v48, v233
	v_sub_f32_e32 v49, v49, v233
	v_sub_f32_e32 v50, v50, v233
	v_sub_f32_e32 v51, v51, v233
	v_sub_f32_e32 v52, v52, v233
	v_sub_f32_e32 v53, v53, v233
	v_sub_f32_e32 v54, v54, v233
	v_sub_f32_e32 v55, v55, v233
	v_sub_f32_e32 v56, v56, v233
	v_sub_f32_e32 v57, v57, v233
	v_sub_f32_e32 v58, v58, v233
	v_sub_f32_e32 v59, v59, v233
	v_sub_f32_e32 v60, v60, v233
	v_sub_f32_e32 v61, v61, v233
	v_sub_f32_e32 v62, v62, v233
	v_sub_f32_e32 v63, v63, v233
	v_sub_f32_e32 v64, v64, v233
	v_sub_f32_e32 v65, v65, v233
	v_sub_f32_e32 v122, 0, v230
	v_mov_b32_e32 v123, v122
	v_mov_b32_e32 v124, v122
	v_mov_b32_e32 v125, v122
	v_mov_b32_e32 v126, v122
	v_mov_b32_e32 v127, v122
	v_mov_b32_e32 v128, v122
	v_mov_b32_e32 v129, v122
	v_mov_b32_e32 v130, v122
	v_mov_b32_e32 v131, v122
	v_mov_b32_e32 v132, v122
	v_mov_b32_e32 v133, v122
	v_mov_b32_e32 v134, v122
	v_mov_b32_e32 v135, v122
	v_mov_b32_e32 v136, v122
	v_mov_b32_e32 v137, v122
	ds_read_b128 v[138:141], v220 offset:13312
	ds_read_b128 v[142:145], v220 offset:19968
	ds_read_b128 v[146:149], v220 offset:13344
	ds_read_b128 v[150:153], v220 offset:20000
	ds_read_b128 v[154:157], v220 offset:13376
	ds_read_b128 v[158:161], v220 offset:20032
	s_movk_i32 s16, 16
